# scan producer (in-loop): lora-up MFMA fragment reads batched per 32x32 block with counted lgkmcnt (3 exposed LDS latencies per block removed)
# speedup vs baseline: 1.0075x; 1.0075x over previous
; __device__ __forceinline__ void scan_chain(const Params& p, int l, int chain, unsigned char* lds) {
;     ...
;     auto process = [&](int c, ScanRaw& R, int cnext) {
;         int len, t0; size_t rbase; chunk_pos(c, len, rbase, t0);
;         int ln_ = lane; asm volatile("" : "+v"(ln_)); const int tl = ln_ >> 3, jg = ln_ & 7, hi = ln_ >> 5, lane = ln_;
;         const int tch = 8 * pw + tl, t = t0 + tch; const size_t row = rbase + t;
;         const float fp = t > 0 ? 1.f : 0.f, fn = t < len - 1 ? 1.f : 0.f;
;         float us[5][8];
; #pragma unroll
;         for (int qn = 0; qn < 5; ++qn) {
;             float z[8], zp[8], zn[8]; unpack8(R.q[qn][0], z); unpack8(R.q[qn][1], zp); unpack8(R.q[qn][2], zn);
;             const float* mup = cst + (5 + qn) * 64 + 8 * jg; const float* mun = cst + (10 + qn) * 64 + 8 * jg;
;             const f32x4 mp0 = *(const f32x4*)mup, mp1 = *(const f32x4*)(mup + 4), mn0 = *(const f32x4*)mun, mn1 = *(const f32x4*)(mun + 4);
; #pragma unroll
;             for (int e = 0; e < 8; ++e) { const float mp = e < 4 ? mp0[e & 3] : mp1[e & 3], mn = e < 4 ? mn0[e & 3] : mn1[e & 3];
;                 us[qn][e] = z[e] + mp * (fp * zp[e] - z[e]) + mn * (fn * zn[e] - z[e]); }
;         }
.LBB0_312:
	s_add_i32 s0, s10, 1
	s_lshl_b32 s1, s0, 5
	s_add_i32 s2, s1, 0xffffff00
	s_cmp_lt_u32 s10, 7
	s_cselect_b64 s[6:7], -1, 0
	s_and_b64 s[12:13], s[6:7], exec
	s_cselect_b32 s14, 0x100, s82
	s_cselect_b32 s1, s1, s2
	s_sub_i32 s2, s14, s1
	s_sub_i32 s2, s2, 32
	s_and_b64 s[12:13], s[68:69], exec
	v_ashrrev_i32_e32 v207, 3, v206
	s_cselect_b32 s1, s1, s2
	v_add_u32_e32 v232, s8, v207
	v_add_u32_e32 v226, s1, v232
	v_cmp_lt_i32_e32 vcc, 0, v226
	s_add_i32 s14, s14, -1
	v_lshlrev_b32_e32 v208, 16, v18
	v_cndmask_b32_e64 v228, 0, 1.0, vcc
	v_cmp_gt_i32_e32 vcc, s14, v226
	v_and_b32_e32 v209, 0xffff0000, v18
	v_lshlrev_b32_e32 v238, 16, v22
	v_and_b32_e32 v239, 0xffff0000, v22
	v_cndmask_b32_e64 v0, 0, 1.0, vcc
	v_lshlrev_b32_e32 v244, 16, v26
	v_and_b32_e32 v245, 0xffff0000, v26
	v_pk_fma_f32 v[238:239], v[228:229], v[238:239], v[208:209] op_sel_hi:[0,1,1] neg_lo:[0,0,1] neg_hi:[0,0,1]
	s_waitcnt lgkmcnt(14)
	v_pk_fma_f32 v[198:199], v[198:199], v[238:239], v[208:209]
	v_pk_fma_f32 v[208:209], v[0:1], v[244:245], v[208:209] op_sel_hi:[0,1,1] neg_lo:[0,0,1] neg_hi:[0,0,1]
	v_pk_fma_f32 v[138:139], v[138:139], v[208:209], v[198:199]
	v_lshlrev_b32_e32 v198, 16, v19
	v_and_b32_e32 v199, 0xffff0000, v19
	v_lshlrev_b32_e32 v208, 16, v23
	v_and_b32_e32 v209, 0xffff0000, v23
	v_lshlrev_b32_e32 v238, 16, v27
	v_and_b32_e32 v239, 0xffff0000, v27
	v_pk_fma_f32 v[208:209], v[228:229], v[208:209], v[198:199] op_sel_hi:[0,1,1] neg_lo:[0,0,1] neg_hi:[0,0,1]
	v_pk_fma_f32 v[200:201], v[200:201], v[208:209], v[198:199]
	v_pk_fma_f32 v[198:199], v[0:1], v[238:239], v[198:199] op_sel_hi:[0,1,1] neg_lo:[0,0,1] neg_hi:[0,0,1]
	v_pk_fma_f32 v[140:141], v[140:141], v[198:199], v[200:201]
	v_lshlrev_b32_e32 v198, 16, v20
	v_and_b32_e32 v199, 0xffff0000, v20
	v_lshlrev_b32_e32 v200, 16, v24
	v_and_b32_e32 v201, 0xffff0000, v24
	v_lshlrev_b32_e32 v208, 16, v28
	v_and_b32_e32 v209, 0xffff0000, v28
	v_pk_fma_f32 v[200:201], v[228:229], v[200:201], v[198:199] op_sel_hi:[0,1,1] neg_lo:[0,0,1] neg_hi:[0,0,1]
	v_pk_fma_f32 v[142:143], v[142:143], v[200:201], v[198:199]
	v_pk_fma_f32 v[198:199], v[0:1], v[208:209], v[198:199] op_sel_hi:[0,1,1] neg_lo:[0,0,1] neg_hi:[0,0,1]
	v_pk_fma_f32 v[142:143], v[194:195], v[198:199], v[142:143]
	v_lshlrev_b32_e32 v194, 16, v21
	v_and_b32_e32 v195, 0xffff0000, v21
	v_lshlrev_b32_e32 v198, 16, v25
	v_and_b32_e32 v199, 0xffff0000, v25
	v_lshlrev_b32_e32 v200, 16, v29
	v_and_b32_e32 v201, 0xffff0000, v29
	v_pk_fma_f32 v[198:199], v[228:229], v[198:199], v[194:195] op_sel_hi:[0,1,1] neg_lo:[0,0,1] neg_hi:[0,0,1]
	v_pk_fma_f32 v[144:145], v[144:145], v[198:199], v[194:195]
	v_pk_fma_f32 v[194:195], v[0:1], v[200:201], v[194:195] op_sel_hi:[0,1,1] neg_lo:[0,0,1] neg_hi:[0,0,1]
	v_pk_fma_f32 v[144:145], v[196:197], v[194:195], v[144:145]
	v_lshlrev_b32_e32 v194, 16, v30
	v_and_b32_e32 v195, 0xffff0000, v30
	v_lshlrev_b32_e32 v196, 16, v34
	v_and_b32_e32 v197, 0xffff0000, v34
	v_lshlrev_b32_e32 v198, 16, v38
	v_and_b32_e32 v199, 0xffff0000, v38
	v_pk_fma_f32 v[196:197], v[228:229], v[196:197], v[194:195] op_sel_hi:[0,1,1] neg_lo:[0,0,1] neg_hi:[0,0,1]
	v_pk_fma_f32 v[186:187], v[186:187], v[196:197], v[194:195]
	v_pk_fma_f32 v[194:195], v[0:1], v[198:199], v[194:195] op_sel_hi:[0,1,1] neg_lo:[0,0,1] neg_hi:[0,0,1]
	s_waitcnt lgkmcnt(13)
	v_pk_fma_f32 v[186:187], v[194:195], v[190:191], v[186:187]
	v_lshlrev_b32_e32 v190, 16, v31
	v_and_b32_e32 v191, 0xffff0000, v31
	v_lshlrev_b32_e32 v194, 16, v35
	v_and_b32_e32 v195, 0xffff0000, v35
	v_lshlrev_b32_e32 v196, 16, v39
	v_and_b32_e32 v197, 0xffff0000, v39
	v_pk_fma_f32 v[194:195], v[228:229], v[194:195], v[190:191] op_sel_hi:[0,1,1] neg_lo:[0,0,1] neg_hi:[0,0,1]
	v_pk_fma_f32 v[188:189], v[188:189], v[194:195], v[190:191]
	v_pk_fma_f32 v[190:191], v[0:1], v[196:197], v[190:191] op_sel_hi:[0,1,1] neg_lo:[0,0,1] neg_hi:[0,0,1]
	v_pk_fma_f32 v[188:189], v[190:191], v[192:193], v[188:189]
	v_lshlrev_b32_e32 v190, 16, v32
	v_and_b32_e32 v191, 0xffff0000, v32
	v_lshlrev_b32_e32 v192, 16, v36
	v_and_b32_e32 v193, 0xffff0000, v36
	v_lshlrev_b32_e32 v194, 16, v40
	v_and_b32_e32 v195, 0xffff0000, v40
	v_pk_fma_f32 v[192:193], v[228:229], v[192:193], v[190:191] op_sel_hi:[0,1,1] neg_lo:[0,0,1] neg_hi:[0,0,1]
	v_pk_fma_f32 v[178:179], v[178:179], v[192:193], v[190:191]
	v_pk_fma_f32 v[190:191], v[0:1], v[194:195], v[190:191] op_sel_hi:[0,1,1] neg_lo:[0,0,1] neg_hi:[0,0,1]
	s_waitcnt lgkmcnt(12)
	v_pk_fma_f32 v[190:191], v[190:191], v[182:183], v[178:179]
	v_lshlrev_b32_e32 v178, 16, v33
	v_and_b32_e32 v179, 0xffff0000, v33
	v_lshlrev_b32_e32 v182, 16, v37
	v_and_b32_e32 v183, 0xffff0000, v37
	v_lshlrev_b32_e32 v192, 16, v41
	v_and_b32_e32 v193, 0xffff0000, v41
	v_pk_fma_f32 v[182:183], v[228:229], v[182:183], v[178:179] op_sel_hi:[0,1,1] neg_lo:[0,0,1] neg_hi:[0,0,1]
	v_pk_fma_f32 v[180:181], v[180:181], v[182:183], v[178:179]
	v_pk_fma_f32 v[178:179], v[0:1], v[192:193], v[178:179] op_sel_hi:[0,1,1] neg_lo:[0,0,1] neg_hi:[0,0,1]
	v_pk_fma_f32 v[182:183], v[178:179], v[184:185], v[180:181]
	v_lshlrev_b32_e32 v178, 16, v42
	v_and_b32_e32 v179, 0xffff0000, v42
	v_lshlrev_b32_e32 v180, 16, v46
	v_and_b32_e32 v181, 0xffff0000, v46
	v_lshlrev_b32_e32 v184, 16, v50
	v_and_b32_e32 v185, 0xffff0000, v50
	v_pk_fma_f32 v[180:181], v[228:229], v[180:181], v[178:179] op_sel_hi:[0,1,1] neg_lo:[0,0,1] neg_hi:[0,0,1]
	s_waitcnt lgkmcnt(11)
	v_pk_fma_f32 v[146:147], v[180:181], v[146:147], v[178:179]
	v_pk_fma_f32 v[178:179], v[0:1], v[184:185], v[178:179] op_sel_hi:[0,1,1] neg_lo:[0,0,1] neg_hi:[0,0,1]
	s_waitcnt lgkmcnt(9)
; __device__ __forceinline__ void scan_chain(const Params& p, int l, int chain, unsigned char* lds) {
;     ...
;         for (int qn = 0; qn < 5; ++qn) {
;             float z[8], zp[8], zn[8]; unpack8(R.q[qn][0], z); unpack8(R.q[qn][1], zp); unpack8(R.q[qn][2], zn);
;             const float* mup = cst + (5 + qn) * 64 + 8 * jg; const float* mun = cst + (10 + qn) * 64 + 8 * jg;
;             const f32x4 mp0 = *(const f32x4*)mup, mp1 = *(const f32x4*)(mup + 4), mn0 = *(const f32x4*)mun, mn1 = *(const f32x4*)(mun + 4);
; #pragma unroll
;             for (int e = 0; e < 8; ++e) { const float mp = e < 4 ? mp0[e & 3] : mp1[e & 3], mn = e < 4 ? mn0[e & 3] : mn1[e & 3];
;                 us[qn][e] = z[e] + mp * (fp * zp[e] - z[e]) + mn * (fn * zn[e] - z[e]); }
;         }
	v_pk_fma_f32 v[146:147], v[178:179], v[174:175], v[146:147]
	v_lshlrev_b32_e32 v174, 16, v43
	v_and_b32_e32 v175, 0xffff0000, v43
	v_lshlrev_b32_e32 v178, 16, v47
	v_and_b32_e32 v179, 0xffff0000, v47
	v_lshlrev_b32_e32 v180, 16, v51
	v_and_b32_e32 v181, 0xffff0000, v51
	v_pk_fma_f32 v[178:179], v[228:229], v[178:179], v[174:175] op_sel_hi:[0,1,1] neg_lo:[0,0,1] neg_hi:[0,0,1]
	v_pk_fma_f32 v[148:149], v[178:179], v[148:149], v[174:175]
	v_pk_fma_f32 v[174:175], v[0:1], v[180:181], v[174:175] op_sel_hi:[0,1,1] neg_lo:[0,0,1] neg_hi:[0,0,1]
	v_pk_fma_f32 v[148:149], v[174:175], v[176:177], v[148:149]
	v_lshlrev_b32_e32 v174, 16, v44
	v_and_b32_e32 v175, 0xffff0000, v44
	v_lshlrev_b32_e32 v176, 16, v48
	v_and_b32_e32 v177, 0xffff0000, v48
	v_lshlrev_b32_e32 v178, 16, v52
	v_and_b32_e32 v179, 0xffff0000, v52
	v_pk_fma_f32 v[176:177], v[228:229], v[176:177], v[174:175] op_sel_hi:[0,1,1] neg_lo:[0,0,1] neg_hi:[0,0,1]
	v_pk_fma_f32 v[150:151], v[176:177], v[150:151], v[174:175]
	v_pk_fma_f32 v[174:175], v[0:1], v[178:179], v[174:175] op_sel_hi:[0,1,1] neg_lo:[0,0,1] neg_hi:[0,0,1]
	s_waitcnt lgkmcnt(8)
	v_pk_fma_f32 v[150:151], v[174:175], v[170:171], v[150:151]
	v_lshlrev_b32_e32 v170, 16, v45
	v_and_b32_e32 v171, 0xffff0000, v45
	v_lshlrev_b32_e32 v174, 16, v49
	v_and_b32_e32 v175, 0xffff0000, v49
	v_lshlrev_b32_e32 v176, 16, v53
	v_and_b32_e32 v177, 0xffff0000, v53
	v_pk_fma_f32 v[174:175], v[228:229], v[174:175], v[170:171] op_sel_hi:[0,1,1] neg_lo:[0,0,1] neg_hi:[0,0,1]
	v_pk_fma_f32 v[152:153], v[174:175], v[152:153], v[170:171]
	v_pk_fma_f32 v[170:171], v[0:1], v[176:177], v[170:171] op_sel_hi:[0,1,1] neg_lo:[0,0,1] neg_hi:[0,0,1]
	v_pk_fma_f32 v[152:153], v[170:171], v[172:173], v[152:153]
	v_lshlrev_b32_e32 v170, 16, v54
	v_lshlrev_b32_e32 v178, 16, v58
	v_and_b32_e32 v171, 0xffff0000, v54
	v_and_b32_e32 v179, 0xffff0000, v58
	v_lshlrev_b32_e32 v194, 16, v62
	v_fma_f32 v178, v228, v178, -v170
	v_lshlrev_b32_e32 v172, 16, v55
	v_lshlrev_b32_e32 v180, 16, v59
	v_and_b32_e32 v195, 0xffff0000, v62
	v_fma_f32 v194, v0, v194, -v170
	s_waitcnt lgkmcnt(7)
	v_fmac_f32_e32 v170, v178, v162
	v_fma_f32 v162, v228, v179, -v171
	v_and_b32_e32 v173, 0xffff0000, v55
	v_and_b32_e32 v181, 0xffff0000, v59
	v_lshlrev_b32_e32 v196, 16, v63
	s_waitcnt lgkmcnt(5)
	v_fmac_f32_e32 v170, v194, v166
	v_fma_f32 v166, v0, v195, -v171
	v_fmac_f32_e32 v171, v162, v163
	v_fma_f32 v162, v228, v180, -v172
	v_lshlrev_b32_e32 v174, 16, v56
	v_lshlrev_b32_e32 v184, 16, v60
	v_and_b32_e32 v197, 0xffff0000, v63
	v_fma_f32 v163, v0, v196, -v172
	v_fmac_f32_e32 v172, v162, v164
	v_fma_f32 v162, v228, v181, -v173
	v_and_b32_e32 v175, 0xffff0000, v56
	v_and_b32_e32 v185, 0xffff0000, v60
	v_lshlrev_b32_e32 v198, 16, v64
	v_fmac_f32_e32 v172, v163, v168
	v_fma_f32 v163, v0, v197, -v173
	v_fmac_f32_e32 v173, v162, v165
	v_fma_f32 v162, v228, v184, -v174
	v_lshlrev_b32_e32 v176, 16, v57
	v_lshlrev_b32_e32 v192, 16, v61
	v_and_b32_e32 v199, 0xffff0000, v64
	v_fmac_f32_e32 v173, v163, v169
	v_fma_f32 v163, v0, v198, -v174
	v_fmac_f32_e32 v174, v162, v154
	v_fma_f32 v154, v228, v185, -v175
	v_and_b32_e32 v177, 0xffff0000, v57
	v_and_b32_e32 v193, 0xffff0000, v61
	v_lshlrev_b32_e32 v200, 16, v65
	s_waitcnt lgkmcnt(4)
	v_fmac_f32_e32 v174, v163, v158
	v_fma_f32 v158, v0, v199, -v175
	v_fmac_f32_e32 v175, v154, v155
	v_fma_f32 v154, v228, v192, -v176
	v_and_b32_e32 v201, 0xffff0000, v65
	v_fma_f32 v155, v0, v200, -v176
	v_fmac_f32_e32 v176, v154, v156
	v_fma_f32 v154, v228, v193, -v177
	v_fmac_f32_e32 v176, v155, v160
	v_fma_f32 v155, v0, v201, -v177
	v_fmac_f32_e32 v177, v154, v157
	v_fmac_f32_e32 v177, v155, v161
	v_lshlrev_b32_e32 v154, 16, v66
	v_and_b32_e32 v155, 0xffff0000, v66
	v_lshlrev_b32_e32 v156, 16, v70
	v_and_b32_e32 v157, 0xffff0000, v70
	v_fmac_f32_e32 v175, v158, v159
	v_lshlrev_b32_e32 v158, 16, v74
	v_and_b32_e32 v159, 0xffff0000, v74
	v_pk_fma_f32 v[156:157], v[228:229], v[156:157], v[154:155] op_sel_hi:[0,1,1] neg_lo:[0,0,1] neg_hi:[0,0,1]
	s_waitcnt lgkmcnt(3)
	v_pk_fma_f32 v[14:15], v[156:157], v[14:15], v[154:155]
	v_pk_fma_f32 v[154:155], v[0:1], v[158:159], v[154:155] op_sel_hi:[0,1,1] neg_lo:[0,0,1] neg_hi:[0,0,1]
	s_waitcnt lgkmcnt(1)
	v_pk_fma_f32 v[10:11], v[154:155], v[10:11], v[14:15]
	v_lshlrev_b32_e32 v14, 16, v67
	v_and_b32_e32 v15, 0xffff0000, v67
	v_lshlrev_b32_e32 v154, 16, v71
	v_and_b32_e32 v155, 0xffff0000, v71
	v_lshlrev_b32_e32 v156, 16, v75
	v_and_b32_e32 v157, 0xffff0000, v75
	v_pk_fma_f32 v[154:155], v[228:229], v[154:155], v[14:15] op_sel_hi:[0,1,1] neg_lo:[0,0,1] neg_hi:[0,0,1]
	v_pk_fma_f32 v[16:17], v[154:155], v[16:17], v[14:15]
	v_pk_fma_f32 v[14:15], v[0:1], v[156:157], v[14:15] op_sel_hi:[0,1,1] neg_lo:[0,0,1] neg_hi:[0,0,1]
	v_pk_fma_f32 v[12:13], v[14:15], v[12:13], v[16:17]
	v_lshlrev_b32_e32 v14, 16, v68
	v_and_b32_e32 v15, 0xffff0000, v68
	v_lshlrev_b32_e32 v16, 16, v72
	v_and_b32_e32 v17, 0xffff0000, v72
	v_lshlrev_b32_e32 v154, 16, v76
	v_and_b32_e32 v155, 0xffff0000, v76
	v_pk_fma_f32 v[16:17], v[228:229], v[16:17], v[14:15] op_sel_hi:[0,1,1] neg_lo:[0,0,1] neg_hi:[0,0,1]
	v_pk_fma_f32 v[6:7], v[16:17], v[6:7], v[14:15]
	v_pk_fma_f32 v[14:15], v[0:1], v[154:155], v[14:15] op_sel_hi:[0,1,1] neg_lo:[0,0,1] neg_hi:[0,0,1]
	s_waitcnt lgkmcnt(0)
; __device__ __forceinline__ u32x4 pack8(const float* f) { u32x4 w; w.x = pk2(f[0], f[1]); w.y = pk2(f[2], f[3]); w.z = pk2(f[4], f[5]); w.w = pk2(f[6], f[7]); return w; }
; __device__ __forceinline__ void scan_chain(const Params& p, int l, int chain, unsigned char* lds) {
;     ...
;         asm volatile("" ::: "memory");
;         if (cnext < NC) load_raw(cnext, R);
;         unsigned char* xs = lds + SC_XS + pw * SC_XSSZ;
;         { float tw[8];
; #pragma unroll
;           for (int e = 0; e < 8; ++e) { const float ex = __expf(2.f * us[3][e]); tw[e] = 1.f - 2.f * __builtin_amdgcn_rcpf(ex + 1.f); }
;           *(u32x4*)(xs + (0 * 8 + tl) * 144 + jg * 16) = pack8(tw); *(u32x4*)(xs + (1 * 8 + tl) * 144 + jg * 16) = pack8(us[4]); }
;         asm volatile("s_waitcnt lgkmcnt(0)" ::: "memory");
;         float* arr = (float*)(lds + SC_BUF + (c & 1) * SC_BUFSZ);
; #pragma unroll
;         for (int m = 0; m < 2; ++m)
; #pragma unroll
;             for (int nb = 0; nb < 2; ++nb) {
;                 f32x16 acc = {};
; #pragma unroll
;                 for (int ks = 0; ks < 4; ++ks) {
;                     const bf16x8 A = *(const bf16x8*)(xs + (m * 8 + (lane & 7)) * 144 + (16 * ks + 8 * hi) * 2);
;                     const bf16x8 B = *(const bf16x8*)(wt + (m * 64 + 32 * nb + (lane & 31)) * 144 + (16 * ks + 8 * hi) * 2);
;                     acc = __builtin_amdgcn_mfma_f32_32x32x16_bf16(A, B, acc, 0, 0, 0);
;                 }
;                 float* dst = arr + (m == 0 ? 0 : 3) * 2048 + (8 * pw + 4 * hi) * 64 + 32 * nb + (lane & 31);
;                 dst[0] = acc[0]; dst[64] = acc[1]; dst[128] = acc[2]; dst[192] = acc[3];
;             }
	v_pk_fma_f32 v[6:7], v[14:15], v[2:3], v[6:7]
	v_lshlrev_b32_e32 v2, 16, v69
	v_and_b32_e32 v3, 0xffff0000, v69
	v_lshlrev_b32_e32 v14, 16, v73
	v_and_b32_e32 v15, 0xffff0000, v73
	v_lshlrev_b32_e32 v16, 16, v77
	v_and_b32_e32 v17, 0xffff0000, v77
	v_pk_fma_f32 v[14:15], v[228:229], v[14:15], v[2:3] op_sel_hi:[0,1,1] neg_lo:[0,0,1] neg_hi:[0,0,1]
	v_fmac_f32_e32 v171, v166, v167
	v_pk_fma_f32 v[8:9], v[14:15], v[8:9], v[2:3]
	v_pk_fma_f32 v[2:3], v[0:1], v[16:17], v[2:3] op_sel_hi:[0,1,1] neg_lo:[0,0,1] neg_hi:[0,0,1]
	v_pk_fma_f32 v[8:9], v[2:3], v[4:5], v[8:9]
	v_add_f32_e32 v2, v170, v170
	v_add_f32_e32 v3, v171, v171
	v_add_f32_e32 v4, v172, v172
	v_add_f32_e32 v5, v173, v173
	v_add_f32_e32 v14, v174, v174
	v_add_f32_e32 v15, v175, v175
	v_mul_f32_e32 v2, 0x3fb8aa3b, v2
	v_mul_f32_e32 v3, 0x3fb8aa3b, v3
	v_mul_f32_e32 v4, 0x3fb8aa3b, v4
	v_mul_f32_e32 v5, 0x3fb8aa3b, v5
	v_mul_f32_e32 v14, 0x3fb8aa3b, v14
	v_mul_f32_e32 v15, 0x3fb8aa3b, v15
	v_add_f32_e32 v16, v176, v176
	v_add_f32_e32 v17, v177, v177
	v_exp_f32_e32 v2, v2
	v_exp_f32_e32 v3, v3
	v_exp_f32_e32 v4, v4
	v_exp_f32_e32 v5, v5
	v_exp_f32_e32 v14, v14
	v_exp_f32_e32 v15, v15
	v_mul_f32_e32 v16, 0x3fb8aa3b, v16
	v_mul_f32_e32 v17, 0x3fb8aa3b, v17
	v_exp_f32_e32 v16, v16
	v_exp_f32_e32 v17, v17
	v_add_f32_e32 v2, 1.0, v2
	v_add_f32_e32 v3, 1.0, v3
	v_add_f32_e32 v4, 1.0, v4
	v_add_f32_e32 v5, 1.0, v5
	v_add_f32_e32 v14, 1.0, v14
	v_add_f32_e32 v15, 1.0, v15
	v_rcp_f32_e32 v2, v2
	v_rcp_f32_e32 v3, v3
	v_rcp_f32_e32 v4, v4
	v_rcp_f32_e32 v5, v5
	v_rcp_f32_e32 v14, v14
	v_rcp_f32_e32 v15, v15
	v_add_f32_e32 v16, 1.0, v16
	v_add_f32_e32 v17, 1.0, v17
	v_rcp_f32_e32 v16, v16
	v_rcp_f32_e32 v17, v17
	v_pk_fma_f32 v[2:3], v[2:3], 2.0, 1.0 op_sel_hi:[1,0,0] neg_lo:[1,0,0] neg_hi:[1,0,0]
	v_pk_fma_f32 v[4:5], v[4:5], 2.0, 1.0 op_sel_hi:[1,0,0] neg_lo:[1,0,0] neg_hi:[1,0,0]
	v_pk_fma_f32 v[14:15], v[14:15], 2.0, 1.0 op_sel_hi:[1,0,0] neg_lo:[1,0,0] neg_hi:[1,0,0]
	v_pk_fma_f32 v[16:17], v[16:17], 2.0, 1.0 op_sel_hi:[1,0,0] neg_lo:[1,0,0] neg_hi:[1,0,0]
	v_cvt_pk_bf16_f32 v2, v2, v3
	v_cvt_pk_bf16_f32 v3, v4, v5
	v_cvt_pk_bf16_f32 v4, v14, v15
	v_mul_lo_u32 v14, v207, s71
	v_lshlrev_b32_e32 v15, 4, v227
	v_cvt_pk_bf16_f32 v5, v16, v17
	v_add3_u32 v14, s9, v14, v15
	s_bitcmp1_b32 s0, 0
	ds_write_b128 v14, v[2:5]
	v_cvt_pk_bf16_f32 v2, v10, v11
	v_cvt_pk_bf16_f32 v3, v12, v13
	v_cvt_pk_bf16_f32 v4, v6, v7
	v_cvt_pk_bf16_f32 v5, v8, v9
	s_cselect_b32 s0, 0xc000, 0
	v_ashrrev_i32_e32 v0, 5, v206
	ds_write_b128 v14, v[2:5] offset:1152
	s_add_i32 s0, s0, 0
	v_and_b32_e32 v3, 31, v206
	v_lshlrev_b32_e32 v2, 4, v0
	v_lshlrev_b32_e32 v0, 10, v0
	s_add_i32 s1, s11, s0
	v_lshlrev_b32_e32 v4, 2, v3
	v_add3_u32 v0, s1, v0, v4
	v_mul_u32_u24_e32 v4, 0x90, v227
	s_waitcnt lgkmcnt(0)
	v_add3_u32 v155, s9, v4, v2
	v_mul_u32_u24_e32 v3, 0x90, v3
	s_add_i32 s1, 0, 0x1c000
	v_add3_u32 v154, s1, v3, v2
	ds_read_b128 v[18:21], v155
	ds_read_b128 v[34:37], v154
	ds_read_b128 v[22:25], v155 offset:32
	ds_read_b128 v[38:41], v154 offset:32
	ds_read_b128 v[26:29], v155 offset:64
	ds_read_b128 v[42:45], v154 offset:64
	ds_read_b128 v[30:33], v155 offset:96
	ds_read_b128 v[46:49], v154 offset:96
	v_lshlrev_b32_e32 v230, 3, v227
	s_mov_b32 s12, 0xbfb8aa3b
	s_mov_b32 s2, 0x800000
	s_mov_b32 s13, 0x3f317217
	s_mov_b32 s14, 0x7f800000
	v_mov_b32_e32 v196, 0x41b17218
	s_waitcnt lgkmcnt(6)
	v_mfma_f32_32x32x16_bf16 v[2:17], v[18:21], v[34:37], 0
	s_waitcnt lgkmcnt(4)
	v_mfma_f32_32x32x16_bf16 v[2:17], v[22:25], v[38:41], v[2:17]
	s_waitcnt lgkmcnt(2)
	v_mfma_f32_32x32x16_bf16 v[2:17], v[26:29], v[42:45], v[2:17]
	s_waitcnt lgkmcnt(0)
	v_mfma_f32_32x32x16_bf16 v[2:17], v[30:33], v[46:49], v[2:17]
	s_nop 11
	ds_write_b32 v0, v2
	ds_write_b32 v0, v3 offset:256
	ds_write_b32 v0, v4 offset:512
	ds_write_b32 v0, v5 offset:768
	ds_read_b128 v[18:21], v155
	ds_read_b128 v[34:37], v154 offset:4608
	ds_read_b128 v[22:25], v155 offset:32
	ds_read_b128 v[38:41], v154 offset:4640
	ds_read_b128 v[26:29], v155 offset:64
	ds_read_b128 v[42:45], v154 offset:4672
	ds_read_b128 v[30:33], v155 offset:96
	ds_read_b128 v[46:49], v154 offset:4704
	s_waitcnt lgkmcnt(6)
	v_mfma_f32_32x32x16_bf16 v[2:17], v[18:21], v[34:37], 0
	s_waitcnt lgkmcnt(4)
	v_mfma_f32_32x32x16_bf16 v[2:17], v[22:25], v[38:41], v[2:17]
	s_waitcnt lgkmcnt(2)
	v_mfma_f32_32x32x16_bf16 v[2:17], v[26:29], v[42:45], v[2:17]
	s_waitcnt lgkmcnt(0)
	v_mfma_f32_32x32x16_bf16 v[2:17], v[30:33], v[46:49], v[2:17]
	s_nop 11
	ds_write_b32 v0, v2 offset:128
	ds_write_b32 v0, v3 offset:384
	ds_write_b32 v0, v4 offset:640
	ds_write_b32 v0, v5 offset:896
	ds_read_b128 v[18:21], v155 offset:1152
	ds_read_b128 v[34:37], v154 offset:9216
	ds_read_b128 v[22:25], v155 offset:1184
	ds_read_b128 v[38:41], v154 offset:9248
	ds_read_b128 v[26:29], v155 offset:1216
	ds_read_b128 v[42:45], v154 offset:9280
	ds_read_b128 v[30:33], v155 offset:1248
	ds_read_b128 v[46:49], v154 offset:9312
	s_waitcnt lgkmcnt(6)
	v_mfma_f32_32x32x16_bf16 v[2:17], v[18:21], v[34:37], 0
	s_waitcnt lgkmcnt(4)
	v_mfma_f32_32x32x16_bf16 v[2:17], v[22:25], v[38:41], v[2:17]
	s_waitcnt lgkmcnt(2)
	v_mfma_f32_32x32x16_bf16 v[2:17], v[26:29], v[42:45], v[2:17]
	s_waitcnt lgkmcnt(0)
	v_mfma_f32_32x32x16_bf16 v[2:17], v[30:33], v[46:49], v[2:17]
	s_nop 11
	ds_write_b32 v0, v2 offset:24576
	ds_write_b32 v0, v3 offset:24832
	ds_write_b32 v0, v4 offset:25088
	ds_write_b32 v0, v5 offset:25344
	ds_read_b128 v[18:21], v155 offset:1152
	ds_read_b128 v[34:37], v154 offset:13824
	ds_read_b128 v[22:25], v155 offset:1184
	ds_read_b128 v[38:41], v154 offset:13856
	ds_read_b128 v[26:29], v155 offset:1216
	ds_read_b128 v[42:45], v154 offset:13888
	ds_read_b128 v[30:33], v155 offset:1248
	ds_read_b128 v[46:49], v154 offset:13920
	v_lshlrev_b32_e32 v154, 2, v230
	s_waitcnt lgkmcnt(6)
; __device__ __forceinline__ void scan_chain(const Params& p, int l, int chain, unsigned char* lds) {
;     ...
;                 for (int ks = 0; ks < 4; ++ks) {
;                     const bf16x8 A = *(const bf16x8*)(xs + (m * 8 + (lane & 7)) * 144 + (16 * ks + 8 * hi) * 2);
;                     const bf16x8 B = *(const bf16x8*)(wt + (m * 64 + 32 * nb + (lane & 31)) * 144 + (16 * ks + 8 * hi) * 2);
;                     acc = __builtin_amdgcn_mfma_f32_32x32x16_bf16(A, B, acc, 0, 0, 0);
;                 }
;                 float* dst = arr + (m == 0 ? 0 : 3) * 2048 + (8 * pw + 4 * hi) * 64 + 32 * nb + (lane & 31);
;                 dst[0] = acc[0]; dst[64] = acc[1]; dst[128] = acc[2]; dst[192] = acc[3];
;             }
;         asm volatile("s_waitcnt lgkmcnt(0)" ::: "memory");
;         float* a0p = arr + tch * 64 + 8 * jg;
;         float wl[8], al[8];
;         { const f32x4 a0 = *(const f32x4*)(a0p), a1 = *(const f32x4*)(a0p + 4), b0 = *(const f32x4*)(a0p + 3 * 2048), b1 = *(const f32x4*)(a0p + 3 * 2048 + 4);
; #pragma unroll
;           for (int e = 0; e < 4; ++e) { wl[e] = a0[e]; wl[4 + e] = a1[e]; al[e] = b0[e]; al[4 + e] = b1[e]; } }
;         float dec[8], kd[8], bv[8], kk[8], av[8]; float n2 = 0.f, bon = 0.f;
;         const float* c_w0 = cst + 0 * 64 + 8 * jg; const float* c_a0 = cst + 1 * 64 + 8 * jg;
;         const float* c_kk = cst + 2 * 64 + 8 * jg; const float* c_ka = cst + 3 * 64 + 8 * jg; const float* c_rk = cst + 4 * 64 + 8 * jg;
; #pragma unroll
;         for (int e = 0; e < 8; ++e) {
;             const float xw = c_w0[e] + wl[e];
;             const float sp = fmaxf(-xw, 0.f) + __logf(1.f + __expf(-fabsf(xw)));
;             dec[e] = __expf(-__expf(-sp - 0.5f));
;             const float a = __builtin_amdgcn_rcpf(1.f + __expf(-(c_a0[e] + al[e])));
;             kk[e] = us[1][e] * c_kk[e]; n2 += kk[e] * kk[e];
;             kd[e] = us[1][e] * (1.f + (a - 1.f) * c_ka[e]);
;             bon += us[0][e] * kd[e] * c_rk[e];
;             av[e] = a;
;         }
	v_mfma_f32_32x32x16_bf16 v[2:17], v[18:21], v[34:37], 0
	s_waitcnt lgkmcnt(4)
	v_mfma_f32_32x32x16_bf16 v[2:17], v[22:25], v[38:41], v[2:17]
	s_waitcnt lgkmcnt(2)
	v_mfma_f32_32x32x16_bf16 v[2:17], v[26:29], v[42:45], v[2:17]
	s_waitcnt lgkmcnt(0)
	v_mfma_f32_32x32x16_bf16 v[2:17], v[30:33], v[46:49], v[2:17]
	s_nop 11
	ds_write_b32 v0, v2 offset:24704
	ds_write_b32 v0, v3 offset:24960
	ds_write_b32 v0, v4 offset:25216
	ds_write_b32 v0, v5 offset:25472
	v_lshlrev_b32_e32 v0, 8, v232
	v_add3_u32 v0, s0, v0, v154
	v_add_u32_e32 v154, 0, v154
	s_waitcnt lgkmcnt(0)
	v_add_u32_e32 v155, 0x22c00, v154
	ds_read_b128 v[2:5], v0
	ds_read_b128 v[10:13], v0 offset:16
	ds_read_b128 v[14:17], v0 offset:24576
	ds_read_b128 v[6:9], v0 offset:24592
	ds_read_b128 v[174:177], v155
	ds_read_b128 v[158:161], v155 offset:16
	v_add_u32_e32 v156, 0x22d00, v154
	ds_read_b128 v[178:181], v156
	ds_read_b128 v[162:165], v156 offset:16
	v_add_u32_e32 v185, 0x22e00, v154
	s_waitcnt lgkmcnt(3)
	v_add_f32_e32 v2, v2, v174
	v_max_f32_e64 v155, -v2, 0
	v_mul_f32_e64 v2, |v2|, s12
	v_exp_f32_e32 v2, v2
	s_waitcnt lgkmcnt(1)
	v_add_f32_e32 v14, v14, v178
	v_mul_f32_e32 v14, 0xbfb8aa3b, v14
	v_exp_f32_e32 v14, v14
	v_add_f32_e32 v2, 1.0, v2
	v_cmp_gt_f32_e32 vcc, s2, v2
	v_add_f32_e32 v3, v3, v175
	v_add_f32_e32 v14, 1.0, v14
	v_cndmask_b32_e64 v157, 0, 32, vcc
	v_ldexp_f32 v2, v2, v157
	v_log_f32_e32 v2, v2
	v_rcp_f32_e32 v174, v14
	v_max_f32_e64 v14, -v3, 0
	v_mul_f32_e64 v3, |v3|, s12
	v_exp_f32_e32 v3, v3
	v_mul_f32_e32 v157, 0x3f317217, v2
	v_fma_f32 v157, v2, s13, -v157
	v_fmac_f32_e32 v157, 0x3377d1cf, v2
	v_fmac_f32_e32 v157, 0x3f317217, v2
	v_cmp_lt_f32_e64 s[0:1], |v2|, s14
	v_add_f32_e32 v3, 1.0, v3
	v_add_u32_e32 v166, 0x22f00, v154
	v_cndmask_b32_e64 v2, v2, v157, s[0:1]
	v_cndmask_b32_e32 v157, 0, v196, vcc
	v_cmp_gt_f32_e32 vcc, s2, v3
	v_add_u32_e32 v154, 0x23000, v154
	v_sub_f32_e32 v2, v2, v157
	v_cndmask_b32_e64 v167, 0, 32, vcc
	v_ldexp_f32 v3, v3, v167
	v_log_f32_e32 v3, v3
	v_add_f32_e32 v2, v155, v2
	ds_read_b128 v[170:173], v154
	ds_read_b128 v[154:157], v154 offset:16
	v_add_f32_e32 v4, v4, v176
	v_mul_f32_e32 v167, 0x3f317217, v3
	v_fma_f32 v167, v3, s13, -v167
	v_fmac_f32_e32 v167, 0x3377d1cf, v3
	v_fmac_f32_e32 v167, 0x3f317217, v3
	v_cmp_lt_f32_e64 s[0:1], |v3|, s14
	v_add_f32_e32 v16, v16, v180
	v_mul_f32_e32 v16, 0xbfb8aa3b, v16
	v_cndmask_b32_e64 v3, v3, v167, s[0:1]
	v_cndmask_b32_e32 v167, 0, v196, vcc
	v_sub_f32_e32 v3, v3, v167
	v_add_f32_e32 v3, v14, v3
	v_add_f32_e32 v14, v15, v179
	v_mul_f32_e32 v14, 0xbfb8aa3b, v14
	v_exp_f32_e32 v14, v14
	ds_read_b128 v[192:195], v166
	ds_read_b128 v[166:169], v166 offset:16
	v_exp_f32_e32 v16, v16
	v_add_f32_e32 v5, v5, v177
	v_add_f32_e32 v14, 1.0, v14
	v_rcp_f32_e32 v175, v14
	v_add_f32_e32 v16, 1.0, v16
	v_rcp_f32_e32 v176, v16
	v_max_f32_e64 v16, -v5, 0
	v_pk_add_f32 v[14:15], v[174:175], -1.0 op_sel_hi:[1,0]
	v_mul_f32_e64 v5, |v5|, s12
	s_waitcnt lgkmcnt(1)
	v_pk_fma_f32 v[14:15], v[192:193], v[14:15], 1.0 op_sel_hi:[1,1,0]
	v_exp_f32_e32 v5, v5
	v_pk_mul_f32 v[14:15], v[186:187], v[14:15]
	v_add_f32_e32 v10, v10, v158
	v_pk_mul_f32 v[178:179], v[138:139], v[14:15]
	v_add_f32_e32 v5, 1.0, v5
	v_fma_f32 v184, v170, v178, 0
	v_max_f32_e64 v170, -v4, 0
	v_mul_f32_e64 v4, |v4|, s12
	v_exp_f32_e32 v4, v4
	v_fmac_f32_e32 v184, v171, v179
	v_max_f32_e64 v158, -v10, 0
	v_mul_f32_e64 v10, |v10|, s12
	v_add_f32_e32 v4, 1.0, v4
	v_cmp_gt_f32_e32 vcc, s2, v4
	v_exp_f32_e32 v10, v10
	v_add_f32_e32 v6, v6, v162
	v_cndmask_b32_e64 v171, 0, 32, vcc
	v_ldexp_f32 v4, v4, v171
	v_log_f32_e32 v4, v4
	v_add_f32_e32 v10, 1.0, v10
	v_mul_f32_e32 v6, 0xbfb8aa3b, v6
	v_exp_f32_e32 v6, v6
	v_mul_f32_e32 v171, 0x3f317217, v4
	v_fma_f32 v171, v4, s13, -v171
	v_fmac_f32_e32 v171, 0x3377d1cf, v4
	v_fmac_f32_e32 v171, 0x3f317217, v4
	v_cmp_lt_f32_e64 s[0:1], |v4|, s14
	v_add_f32_e32 v6, 1.0, v6
	v_add_f32_e32 v12, v12, v160
	v_cndmask_b32_e64 v4, v4, v171, s[0:1]
	v_cndmask_b32_e32 v171, 0, v196, vcc
	v_sub_f32_e32 v4, v4, v171
	v_cmp_gt_f32_e32 vcc, s2, v5
	v_add_f32_e32 v4, v170, v4
	v_add_f32_e32 v8, v8, v164
	v_cndmask_b32_e64 v170, 0, 32, vcc
	v_ldexp_f32 v5, v5, v170
	v_log_f32_e32 v5, v5
	v_mul_f32_e32 v8, 0xbfb8aa3b, v8
	v_exp_f32_e32 v8, v8
	v_sub_f32_e32 v2, -0.5, v2
	v_mul_f32_e32 v170, 0x3f317217, v5
	v_fma_f32 v170, v5, s13, -v170
	v_fmac_f32_e32 v170, 0x3377d1cf, v5
	v_fmac_f32_e32 v170, 0x3f317217, v5
	v_cmp_lt_f32_e64 s[0:1], |v5|, s14
	v_add_f32_e32 v8, 1.0, v8
	v_sub_f32_e32 v3, -0.5, v3
	v_cndmask_b32_e64 v5, v5, v170, s[0:1]
	v_cndmask_b32_e32 v170, 0, v196, vcc
	v_sub_f32_e32 v5, v5, v170
	v_add_f32_e32 v5, v16, v5
	v_add_f32_e32 v16, v17, v181
	v_mul_f32_e32 v16, 0xbfb8aa3b, v16
	v_exp_f32_e32 v16, v16
	v_cmp_gt_f32_e32 vcc, s2, v10
	v_sub_f32_e32 v4, -0.5, v4
	v_sub_f32_e32 v5, -0.5, v5
	v_add_f32_e32 v16, 1.0, v16
	v_rcp_f32_e32 v177, v16
	v_mul_f32_e32 v2, 0x3fb8aa3b, v2
	v_mul_f32_e32 v3, 0x3fb8aa3b, v3
	v_mul_f32_e32 v4, 0x3fb8aa3b, v4
	v_pk_add_f32 v[16:17], v[176:177], -1.0 op_sel_hi:[1,0]
	v_mul_f32_e32 v5, 0x3fb8aa3b, v5
	v_pk_fma_f32 v[16:17], v[194:195], v[16:17], 1.0 op_sel_hi:[1,1,0]
	v_exp_f32_e32 v2, v2
	v_pk_mul_f32 v[16:17], v[188:189], v[16:17]
	v_exp_f32_e32 v3, v3
	v_pk_mul_f32 v[170:171], v[140:141], v[16:17]
	v_exp_f32_e32 v4, v4
	v_fmac_f32_e32 v184, v172, v170
	v_cndmask_b32_e64 v170, 0, 32, vcc
	v_ldexp_f32 v10, v10, v170
	v_log_f32_e32 v10, v10
	v_fmac_f32_e32 v184, v173, v171
	v_exp_f32_e32 v5, v5
	v_mul_f32_e32 v2, 0xbfb8aa3b, v2
	v_mul_f32_e32 v170, 0x3f317217, v10
	v_fma_f32 v170, v10, s13, -v170
	v_fmac_f32_e32 v170, 0x3377d1cf, v10
	v_fmac_f32_e32 v170, 0x3f317217, v10
; __device__ __forceinline__ void scan_chain(const Params& p, int l, int chain, unsigned char* lds) {
;     ...
; #pragma unroll
;         for (int e = 0; e < 8; ++e) {
;             const float xw = c_w0[e] + wl[e];
;             const float sp = fmaxf(-xw, 0.f) + __logf(1.f + __expf(-fabsf(xw)));
;             dec[e] = __expf(-__expf(-sp - 0.5f));
;             const float a = __builtin_amdgcn_rcpf(1.f + __expf(-(c_a0[e] + al[e])));
;             kk[e] = us[1][e] * c_kk[e]; n2 += kk[e] * kk[e];
;             kd[e] = us[1][e] * (1.f + (a - 1.f) * c_ka[e]);
;             bon += us[0][e] * kd[e] * c_rk[e];
;             av[e] = a;
;         }
	v_cmp_lt_f32_e64 s[0:1], |v10|, s14
	v_mul_f32_e32 v3, 0xbfb8aa3b, v3
	v_mul_f32_e32 v4, 0xbfb8aa3b, v4
	v_cndmask_b32_e64 v10, v10, v170, s[0:1]
	v_cndmask_b32_e32 v170, 0, v196, vcc
	v_sub_f32_e32 v10, v10, v170
	v_add_f32_e32 v10, v158, v10
	v_rcp_f32_e32 v158, v6
	v_add_f32_e32 v6, v11, v159
	v_max_f32_e64 v11, -v6, 0
	v_mul_f32_e64 v6, |v6|, s12
	v_exp_f32_e32 v6, v6
	ds_read_b128 v[170:173], v185
	ds_read_b128 v[178:181], v185 offset:16
	v_sub_f32_e32 v10, -0.5, v10
	v_mul_f32_e32 v10, 0x3fb8aa3b, v10
	v_add_f32_e32 v6, 1.0, v6
	v_cmp_gt_f32_e32 vcc, s2, v6
	v_exp_f32_e32 v10, v10
	v_mul_f32_e32 v5, 0xbfb8aa3b, v5
	v_cndmask_b32_e64 v159, 0, 32, vcc
	v_ldexp_f32 v6, v6, v159
	v_log_f32_e32 v6, v6
	v_exp_f32_e32 v2, v2
	v_exp_f32_e32 v3, v3
	v_exp_f32_e32 v4, v4
	v_mul_f32_e32 v159, 0x3f317217, v6
	v_fma_f32 v159, v6, s13, -v159
	v_fmac_f32_e32 v159, 0x3377d1cf, v6
	v_fmac_f32_e32 v159, 0x3f317217, v6
	v_cmp_lt_f32_e64 s[0:1], |v6|, s14
	v_exp_f32_e32 v5, v5
	v_mul_f32_e32 v10, 0xbfb8aa3b, v10
	v_cndmask_b32_e64 v6, v6, v159, s[0:1]
	v_cndmask_b32_e32 v159, 0, v196, vcc
	v_sub_f32_e32 v6, v6, v159
	v_add_f32_e32 v6, v11, v6
	v_sub_f32_e32 v6, -0.5, v6
	v_mul_f32_e32 v6, 0x3fb8aa3b, v6
	v_exp_f32_e32 v6, v6
	v_exp_f32_e32 v10, v10
	v_mul_f32_e32 v6, 0xbfb8aa3b, v6
	v_exp_f32_e32 v11, v6
	v_add_f32_e32 v6, v7, v163
	v_mul_f32_e32 v6, 0xbfb8aa3b, v6
	v_exp_f32_e32 v6, v6
	s_waitcnt lgkmcnt(0)
; __device__ __forceinline__ float sum8(float v) { v += dpp_xor1(v); v += dpp_xor2(v); v += dpp_hmir(v); return v; }
; __device__ __forceinline__ void scan_chain(const Params& p, int l, int chain, unsigned char* lds) {
;     ...
;         for (int e = 0; e < 8; ++e) {
;             const float xw = c_w0[e] + wl[e];
;             const float sp = fmaxf(-xw, 0.f) + __logf(1.f + __expf(-fabsf(xw)));
;             dec[e] = __expf(-__expf(-sp - 0.5f));
;             const float a = __builtin_amdgcn_rcpf(1.f + __expf(-(c_a0[e] + al[e])));
;             kk[e] = us[1][e] * c_kk[e]; n2 += kk[e] * kk[e];
;             kd[e] = us[1][e] * (1.f + (a - 1.f) * c_ka[e]);
;             bon += us[0][e] * kd[e] * c_rk[e];
;             av[e] = a;
;         }
;         n2 = sum8(n2); bon = sum8(bon);
;         const float rn = 1.f / fmaxf(sqrtf(n2), 1e-12f);
; #pragma unroll
;         for (int e = 0; e < 8; ++e) { kk[e] *= rn; bv[e] = kk[e] * av[e]; kk[e] = -kk[e]; }
;         *(f32x4*)(a0p + 0 * 2048) = (f32x4){dec[0], dec[1], dec[2], dec[3]}; *(f32x4*)(a0p + 0 * 2048 + 4) = (f32x4){dec[4], dec[5], dec[6], dec[7]};
;         *(f32x4*)(a0p + 1 * 2048) = (f32x4){kd[0], kd[1], kd[2], kd[3]};     *(f32x4*)(a0p + 1 * 2048 + 4) = (f32x4){kd[4], kd[5], kd[6], kd[7]};
;         *(f32x4*)(a0p + 2 * 2048) = (f32x4){kk[0], kk[1], kk[2], kk[3]};     *(f32x4*)(a0p + 2 * 2048 + 4) = (f32x4){kk[4], kk[5], kk[6], kk[7]};
;         *(f32x4*)(a0p + 3 * 2048) = (f32x4){bv[0], bv[1], bv[2], bv[3]};     *(f32x4*)(a0p + 3 * 2048 + 4) = (f32x4){bv[4], bv[5], bv[6], bv[7]};
;         *(f32x4*)(a0p + 4 * 2048) = (f32x4){us[0][0], us[0][1], us[0][2], us[0][3]}; *(f32x4*)(a0p + 4 * 2048 + 4) = (f32x4){us[0][4], us[0][5], us[0][6], us[0][7]};
;         *(f32x4*)(a0p + 5 * 2048) = (f32x4){us[2][0], us[2][1], us[2][2], us[2][3]}; *(f32x4*)(a0p + 5 * 2048 + 4) = (f32x4){us[2][4], us[2][5], us[2][6], us[2][7]};
;         if (jg == 0) bs[((size_t)dir * T + row) * 8 + h] = bon;
	v_pk_mul_f32 v[162:163], v[190:191], v[178:179]
	v_add_f32_e32 v6, 1.0, v6
	v_rcp_f32_e32 v159, v6
	v_pk_mul_f32 v[178:179], v[162:163], v[162:163]
	v_pk_add_f32 v[6:7], v[158:159], -1.0 op_sel_hi:[1,0]
	s_nop 0
	v_pk_fma_f32 v[6:7], v[166:167], v[6:7], 1.0 op_sel_hi:[1,1,0]
	s_nop 0
	v_pk_mul_f32 v[6:7], v[190:191], v[6:7]
	s_nop 0
	v_pk_mul_f32 v[166:167], v[142:143], v[6:7]
	s_nop 0
	v_fmac_f32_e32 v184, v154, v166
	v_max_f32_e64 v154, -v12, 0
	v_mul_f32_e64 v12, |v12|, s12
	v_exp_f32_e32 v12, v12
	v_fmac_f32_e32 v184, v155, v167
	v_add_f32_e32 v12, 1.0, v12
	v_cmp_gt_f32_e32 vcc, s2, v12
	s_nop 1
	v_cndmask_b32_e64 v155, 0, 32, vcc
	v_ldexp_f32 v12, v12, v155
	v_log_f32_e32 v12, v12
	s_nop 0
	v_mul_f32_e32 v155, 0x3f317217, v12
	v_fma_f32 v155, v12, s13, -v155
	v_fmac_f32_e32 v155, 0x3377d1cf, v12
	v_fmac_f32_e32 v155, 0x3f317217, v12
	v_cmp_lt_f32_e64 s[0:1], |v12|, s14
	s_nop 1
	v_cndmask_b32_e64 v12, v12, v155, s[0:1]
	v_cndmask_b32_e32 v155, 0, v196, vcc
	v_sub_f32_e32 v12, v12, v155
	v_add_f32_e32 v12, v154, v12
	v_rcp_f32_e32 v154, v8
	v_add_f32_e32 v8, v13, v161
	v_max_f32_e64 v13, -v8, 0
	v_mul_f32_e64 v8, |v8|, s12
	v_exp_f32_e32 v8, v8
	v_pk_mul_f32 v[160:161], v[182:183], v[180:181]
	v_sub_f32_e32 v12, -0.5, v12
	v_mul_f32_e32 v12, 0x3fb8aa3b, v12
	v_add_f32_e32 v8, 1.0, v8
	v_cmp_gt_f32_e32 vcc, s2, v8
	v_exp_f32_e32 v12, v12
	s_nop 0
	v_cndmask_b32_e64 v155, 0, 32, vcc
	v_ldexp_f32 v8, v8, v155
	v_log_f32_e32 v8, v8
	v_mul_f32_e32 v12, 0xbfb8aa3b, v12
	v_exp_f32_e32 v12, v12
	v_mul_f32_e32 v155, 0x3f317217, v8
	v_fma_f32 v155, v8, s13, -v155
	v_fmac_f32_e32 v155, 0x3377d1cf, v8
	v_fmac_f32_e32 v155, 0x3f317217, v8
	v_cmp_lt_f32_e64 s[0:1], |v8|, s14
	s_nop 1
	v_cndmask_b32_e64 v8, v8, v155, s[0:1]
	v_cndmask_b32_e32 v155, 0, v196, vcc
	v_sub_f32_e32 v8, v8, v155
	v_add_f32_e32 v8, v13, v8
	v_sub_f32_e32 v8, -0.5, v8
	v_mul_f32_e32 v8, 0x3fb8aa3b, v8
	v_exp_f32_e32 v8, v8
	s_mov_b32 s0, 0xf800000
	v_mul_f32_e32 v8, 0xbfb8aa3b, v8
	v_exp_f32_e32 v13, v8
	v_add_f32_e32 v8, v9, v165
	v_mul_f32_e32 v8, 0xbfb8aa3b, v8
	v_exp_f32_e32 v8, v8
	v_pk_mul_f32 v[164:165], v[160:161], v[160:161]
	v_add_f32_e32 v8, 1.0, v8
	v_rcp_f32_e32 v155, v8
	s_nop 0
	v_pk_add_f32 v[8:9], v[154:155], -1.0 op_sel_hi:[1,0]
	s_nop 0
	v_pk_fma_f32 v[8:9], v[168:169], v[8:9], 1.0 op_sel_hi:[1,1,0]
	s_nop 0
	v_pk_mul_f32 v[8:9], v[182:183], v[8:9]
	ds_write_b128 v0, v[2:5]
	ds_write_b128 v0, v[10:13] offset:16
	ds_write_b128 v0, v[14:17] offset:8192
	ds_write_b128 v0, v[6:9] offset:8208
	v_pk_mul_f32 v[166:167], v[144:145], v[8:9]
	s_nop 0
	v_fmac_f32_e32 v184, v156, v166
	v_fmac_f32_e32 v184, v157, v167
	v_pk_mul_f32 v[166:167], v[186:187], v[170:171]
	v_pk_mul_f32 v[170:171], v[188:189], v[172:173]
	v_pk_mul_f32 v[168:169], v[166:167], v[166:167]
	v_pk_mul_f32 v[172:173], v[170:171], v[170:171]
	v_add_f32_e32 v168, v168, v169
	v_add_f32_e32 v168, v168, v172
	v_add_f32_e32 v168, v168, v173
	v_add_f32_e32 v168, v168, v178
	v_add_f32_e32 v168, v168, v179
	v_add_f32_e32 v164, v168, v164
	v_add_f32_e32 v164, v164, v165
	v_add_f32_dpp v156, v184, v184 quad_perm:[1,0,3,2] row_mask:0xf bank_mask:0xf bound_ctrl:1
	s_nop 0
	v_add_f32_dpp v164, v164, v164 quad_perm:[1,0,3,2] row_mask:0xf bank_mask:0xf bound_ctrl:1
	v_add_f32_dpp v156, v156, v156 quad_perm:[2,3,0,1] row_mask:0xf bank_mask:0xf bound_ctrl:1
	s_nop 0
	v_add_f32_dpp v164, v164, v164 quad_perm:[2,3,0,1] row_mask:0xf bank_mask:0xf bound_ctrl:1
	v_mov_b32_dpp v157, v156 row_half_mirror row_mask:0xf bank_mask:0xf bound_ctrl:1
	s_nop 0
	v_add_f32_dpp v164, v164, v164 row_half_mirror row_mask:0xf bank_mask:0xf bound_ctrl:1
	v_cmp_gt_f32_e32 vcc, s0, v164
	v_mul_f32_e32 v165, 0x4f800000, v164
	s_nop 0
	v_cndmask_b32_e32 v164, v164, v165, vcc
	v_sqrt_f32_e32 v165, v164
	s_nop 0
	v_add_u32_e32 v168, -1, v165
	v_fma_f32 v169, -v168, v165, v164
	v_cmp_ge_f32_e64 s[0:1], 0, v169
	v_add_u32_e32 v169, 1, v165
	s_nop 0
	v_cndmask_b32_e64 v168, v165, v168, s[0:1]
	v_fma_f32 v165, -v169, v165, v164
	v_cmp_lt_f32_e64 s[0:1], 0, v165
	s_nop 1
	v_cndmask_b32_e64 v165, v168, v169, s[0:1]
	v_mul_f32_e32 v168, 0x37800000, v165
	v_cndmask_b32_e32 v165, v165, v168, vcc
	v_mov_b32_e32 v168, 0x260
	v_cmp_class_f32_e32 vcc, v164, v168
	s_nop 1
	v_cndmask_b32_e32 v164, v165, v164, vcc
	v_max_f32_e32 v164, 0x2b8cbccc, v164
	v_div_scale_f32 v165, s[0:1], v164, v164, 1.0
	v_rcp_f32_e32 v168, v165
	s_nop 0
	v_fma_f32 v169, -v165, v168, 1.0
	v_fmac_f32_e32 v168, v169, v168
	v_div_scale_f32 v169, vcc, 1.0, v164, 1.0
	v_mul_f32_e32 v172, v169, v168
	v_fma_f32 v173, -v165, v172, v169
	v_fmac_f32_e32 v172, v173, v168
	v_fma_f32 v165, -v165, v172, v169
	v_div_fmas_f32 v165, v165, v168, v172
	v_div_fixup_f32 v164, v165, v164, 1.0
	v_pk_mul_f32 v[166:167], v[166:167], v[164:165] op_sel_hi:[1,0]
	v_pk_mul_f32 v[168:169], v[170:171], v[164:165] op_sel_hi:[1,0]
	v_pk_mul_f32 v[162:163], v[162:163], v[164:165] op_sel_hi:[1,0]
	v_pk_mul_f32 v[160:161], v[160:161], v[164:165] op_sel_hi:[1,0]
	v_xor_b32_e32 v5, 0x80000000, v169
	v_xor_b32_e32 v4, 0x80000000, v168
	v_xor_b32_e32 v3, 0x80000000, v167
	v_xor_b32_e32 v2, 0x80000000, v166
	ds_write_b128 v0, v[2:5] offset:16384
	v_xor_b32_e32 v5, 0x80000000, v161
	v_xor_b32_e32 v4, 0x80000000, v160
	v_xor_b32_e32 v3, 0x80000000, v163
	v_xor_b32_e32 v2, 0x80000000, v162
	ds_write_b128 v0, v[2:5] offset:16400
	v_pk_mul_f32 v[2:3], v[174:175], v[166:167]
	v_pk_mul_f32 v[4:5], v[176:177], v[168:169]
	ds_write_b128 v0, v[2:5] offset:24576
	v_pk_mul_f32 v[2:3], v[158:159], v[162:163]
	v_pk_mul_f32 v[4:5], v[154:155], v[160:161]
	v_cmp_eq_u32_e32 vcc, 0, v227
	ds_write_b128 v0, v[2:5] offset:24592
	ds_write_b128 v0, v[138:141] offset:32768
	ds_write_b128 v0, v[142:145] offset:32784
	ds_write_b128 v0, v[146:149] offset:40960
	ds_write_b128 v0, v[150:153] offset:40976
	s_and_saveexec_b64 s[0:1], vcc
	s_cbranch_execz .LBB0_314
	s_and_b64 s[6:7], s[6:7], exec
	v_readlane_b32 s6, v252, 52
	v_readlane_b32 s2, v251, 18
	s_cselect_b32 s2, s6, s2
	v_readlane_b32 s6, v251, 7
	v_ashrrev_i32_e32 v227, 31, v226
	v_readlane_b32 s7, v252, 53
	s_add_i32 s2, s2, s6
	v_lshl_add_u64 v[2:3], s[2:3], 0, v[226:227]
	v_readlane_b32 s6, v251, 10
	v_lshlrev_b64 v[2:3], 5, v[2:3]
	v_readlane_b32 s7, v251, 11
	v_add_f32_e32 v0, v156, v157
	s_nop 0
	v_lshl_add_u64 v[2:3], s[6:7], 0, v[2:3]
	global_store_dword v[2:3], v0, off
